# scan loop pk3 with s_nop before first DPP (hazard-clean)
# speedup vs baseline: 1.0017x; 1.0017x over previous
.Lscan_iter:
	ds_read_b128 v[26:29], v118 offset:40960
	ds_read_b128 v[30:33], v118 offset:40976
	ds_read_b128 v[76:79], v118 offset:16384
	ds_read_b128 v[80:83], v118 offset:16400
	ds_read2_b32 v[34:35], v119 offset0:0 offset1:32
	ds_read2_b32 v[0:1], v121 offset0:0 offset1:32
	ds_read_b128 v[18:21], v118 offset:8192
	ds_read_b128 v[22:25], v118 offset:8208
	s_waitcnt lgkmcnt(8)
	v_pk_mul_f32 v[84:85], v[60:61], v[2:3] op_sel:[0,0] op_sel_hi:[1,0]
	v_pk_mul_f32 v[86:87], v[60:61], v[10:11] op_sel:[0,0] op_sel_hi:[1,0]
	v_pk_fma_f32 v[84:85], v[62:63], v[2:3], v[84:85] op_sel:[0,1,0] op_sel_hi:[1,1,1]
	v_pk_fma_f32 v[86:87], v[62:63], v[10:11], v[86:87] op_sel:[0,1,0] op_sel_hi:[1,1,1]
	v_pk_fma_f32 v[84:85], v[64:65], v[4:5], v[84:85] op_sel:[0,0,0] op_sel_hi:[1,0,1]
	v_pk_fma_f32 v[86:87], v[64:65], v[12:13], v[86:87] op_sel:[0,0,0] op_sel_hi:[1,0,1]
	v_pk_fma_f32 v[84:85], v[66:67], v[4:5], v[84:85] op_sel:[0,1,0] op_sel_hi:[1,1,1]
	v_pk_fma_f32 v[86:87], v[66:67], v[12:13], v[86:87] op_sel:[0,1,0] op_sel_hi:[1,1,1]
	v_pk_fma_f32 v[84:85], v[68:69], v[6:7], v[84:85] op_sel:[0,0,0] op_sel_hi:[1,0,1]
	v_pk_fma_f32 v[86:87], v[68:69], v[14:15], v[86:87] op_sel:[0,0,0] op_sel_hi:[1,0,1]
	v_pk_fma_f32 v[84:85], v[70:71], v[6:7], v[84:85] op_sel:[0,1,0] op_sel_hi:[1,1,1]
	v_pk_fma_f32 v[86:87], v[70:71], v[14:15], v[86:87] op_sel:[0,1,0] op_sel_hi:[1,1,1]
	v_pk_fma_f32 v[84:85], v[72:73], v[8:9], v[84:85] op_sel:[0,0,0] op_sel_hi:[1,0,1]
	v_pk_fma_f32 v[86:87], v[72:73], v[16:17], v[86:87] op_sel:[0,0,0] op_sel_hi:[1,0,1]
	v_pk_fma_f32 v[84:85], v[74:75], v[8:9], v[84:85] op_sel:[0,1,0] op_sel_hi:[1,1,1]
	v_pk_fma_f32 v[86:87], v[74:75], v[16:17], v[86:87] op_sel:[0,1,0] op_sel_hi:[1,1,1]
	s_nop 0
	v_add_f32_dpp v84, v84, v84 quad_perm:[1,0,3,2] row_mask:0xf bank_mask:0xf bound_ctrl:1
	v_add_f32_dpp v85, v85, v85 quad_perm:[1,0,3,2] row_mask:0xf bank_mask:0xf bound_ctrl:1
	v_add_f32_dpp v86, v86, v86 quad_perm:[1,0,3,2] row_mask:0xf bank_mask:0xf bound_ctrl:1
	v_add_f32_dpp v87, v87, v87 quad_perm:[1,0,3,2] row_mask:0xf bank_mask:0xf bound_ctrl:1
	v_add_f32_dpp v84, v84, v84 quad_perm:[2,3,0,1] row_mask:0xf bank_mask:0xf bound_ctrl:1
	v_add_f32_dpp v85, v85, v85 quad_perm:[2,3,0,1] row_mask:0xf bank_mask:0xf bound_ctrl:1
	v_add_f32_dpp v86, v86, v86 quad_perm:[2,3,0,1] row_mask:0xf bank_mask:0xf bound_ctrl:1
	v_add_f32_dpp v87, v87, v87 quad_perm:[2,3,0,1] row_mask:0xf bank_mask:0xf bound_ctrl:1
	v_add_f32_dpp v84, v84, v84 row_half_mirror row_mask:0xf bank_mask:0xf bound_ctrl:1
	v_add_f32_dpp v85, v85, v85 row_half_mirror row_mask:0xf bank_mask:0xf bound_ctrl:1
	v_add_f32_dpp v86, v86, v86 row_half_mirror row_mask:0xf bank_mask:0xf bound_ctrl:1
	v_add_f32_dpp v87, v87, v87 row_half_mirror row_mask:0xf bank_mask:0xf bound_ctrl:1
	ds_read_b128 v[2:5], v118 offset:33024
	ds_read_b128 v[6:9], v118 offset:33040
	ds_read_b128 v[10:13], v118 offset:256
	ds_read_b128 v[14:17], v118 offset:272
	s_waitcnt lgkmcnt(10)
	v_pk_mul_f32 v[114:115], v[26:27], v[84:85] op_sel:[0,0] op_sel_hi:[0,1] neg_lo:[0,1] neg_hi:[0,1]
	v_pk_mul_f32 v[116:117], v[26:27], v[84:85] op_sel:[1,0] op_sel_hi:[1,1] neg_lo:[0,1] neg_hi:[0,1]
	v_pk_mul_f32 v[122:123], v[28:29], v[84:85] op_sel:[0,0] op_sel_hi:[0,1] neg_lo:[0,1] neg_hi:[0,1]
	v_pk_mul_f32 v[124:125], v[28:29], v[84:85] op_sel:[1,0] op_sel_hi:[1,1] neg_lo:[0,1] neg_hi:[0,1]
	v_pk_mul_f32 v[126:127], v[30:31], v[84:85] op_sel:[0,0] op_sel_hi:[0,1] neg_lo:[0,1] neg_hi:[0,1]
	v_pk_mul_f32 v[128:129], v[30:31], v[84:85] op_sel:[1,0] op_sel_hi:[1,1] neg_lo:[0,1] neg_hi:[0,1]
	v_pk_mul_f32 v[130:131], v[32:33], v[84:85] op_sel:[0,0] op_sel_hi:[0,1] neg_lo:[0,1] neg_hi:[0,1]
	v_pk_mul_f32 v[132:133], v[32:33], v[84:85] op_sel:[1,0] op_sel_hi:[1,1] neg_lo:[0,1] neg_hi:[0,1]
	s_waitcnt lgkmcnt(7)
	v_pk_fma_f32 v[114:115], v[76:77], v[34:35], v[114:115] op_sel:[0,0,0] op_sel_hi:[0,1,1]
	v_pk_fma_f32 v[116:117], v[76:77], v[34:35], v[116:117] op_sel:[1,0,0] op_sel_hi:[1,1,1]
	v_pk_fma_f32 v[122:123], v[78:79], v[34:35], v[122:123] op_sel:[0,0,0] op_sel_hi:[0,1,1]
	v_pk_fma_f32 v[124:125], v[78:79], v[34:35], v[124:125] op_sel:[1,0,0] op_sel_hi:[1,1,1]
	v_pk_fma_f32 v[126:127], v[80:81], v[34:35], v[126:127] op_sel:[0,0,0] op_sel_hi:[0,1,1]
	v_pk_fma_f32 v[128:129], v[80:81], v[34:35], v[128:129] op_sel:[1,0,0] op_sel_hi:[1,1,1]
	v_pk_fma_f32 v[130:131], v[82:83], v[34:35], v[130:131] op_sel:[0,0,0] op_sel_hi:[0,1,1]
	v_pk_fma_f32 v[132:133], v[82:83], v[34:35], v[132:133] op_sel:[1,0,0] op_sel_hi:[1,1,1]
	s_waitcnt lgkmcnt(6)
	v_pk_fma_f32 v[86:87], v[84:85], v[0:1], v[86:87] op_sel:[0,0,0] op_sel_hi:[1,0,1] neg_lo:[1,0,0] neg_hi:[1,0,0]
	v_pk_fma_f32 v[86:87], v[34:35], v[0:1], v[86:87] op_sel:[0,1,0] op_sel_hi:[1,1,1]
	s_mov_b64 exec, s[8:9]
	ds_write2_b32 v120, v86, v87 offset0:0 offset1:32
	s_mov_b64 exec, -1
	s_waitcnt lgkmcnt(5)
	v_pk_fma_f32 v[60:61], v[60:61], v[18:19], v[114:115] op_sel:[0,0,0] op_sel_hi:[1,0,1]
	v_pk_fma_f32 v[62:63], v[62:63], v[18:19], v[116:117] op_sel:[0,1,0] op_sel_hi:[1,1,1]
	v_pk_fma_f32 v[64:65], v[64:65], v[20:21], v[122:123] op_sel:[0,0,0] op_sel_hi:[1,0,1]
	v_pk_fma_f32 v[66:67], v[66:67], v[20:21], v[124:125] op_sel:[0,1,0] op_sel_hi:[1,1,1]
	v_pk_fma_f32 v[68:69], v[68:69], v[22:23], v[126:127] op_sel:[0,0,0] op_sel_hi:[1,0,1]
	v_pk_fma_f32 v[70:71], v[70:71], v[22:23], v[128:129] op_sel:[0,1,0] op_sel_hi:[1,1,1]
	v_pk_fma_f32 v[72:73], v[72:73], v[24:25], v[130:131] op_sel:[0,0,0] op_sel_hi:[1,0,1]
	v_pk_fma_f32 v[74:75], v[74:75], v[24:25], v[132:133] op_sel:[0,1,0] op_sel_hi:[1,1,1]
	ds_read_b128 v[26:29], v118 offset:41216
	ds_read_b128 v[30:33], v118 offset:41232
	ds_read_b128 v[76:79], v118 offset:16640
	ds_read_b128 v[80:83], v118 offset:16656
	ds_read2_b32 v[34:35], v119 offset0:64 offset1:96
	ds_read2_b32 v[0:1], v121 offset0:1 offset1:33
	ds_read_b128 v[18:21], v118 offset:8448
	ds_read_b128 v[22:25], v118 offset:8464
	s_waitcnt lgkmcnt(8)
	v_pk_mul_f32 v[84:85], v[60:61], v[2:3] op_sel:[0,0] op_sel_hi:[1,0]
	v_pk_mul_f32 v[86:87], v[60:61], v[10:11] op_sel:[0,0] op_sel_hi:[1,0]
	v_pk_fma_f32 v[84:85], v[62:63], v[2:3], v[84:85] op_sel:[0,1,0] op_sel_hi:[1,1,1]
	v_pk_fma_f32 v[86:87], v[62:63], v[10:11], v[86:87] op_sel:[0,1,0] op_sel_hi:[1,1,1]
	v_pk_fma_f32 v[84:85], v[64:65], v[4:5], v[84:85] op_sel:[0,0,0] op_sel_hi:[1,0,1]
	v_pk_fma_f32 v[86:87], v[64:65], v[12:13], v[86:87] op_sel:[0,0,0] op_sel_hi:[1,0,1]
	v_pk_fma_f32 v[84:85], v[66:67], v[4:5], v[84:85] op_sel:[0,1,0] op_sel_hi:[1,1,1]
	v_pk_fma_f32 v[86:87], v[66:67], v[12:13], v[86:87] op_sel:[0,1,0] op_sel_hi:[1,1,1]
	v_pk_fma_f32 v[84:85], v[68:69], v[6:7], v[84:85] op_sel:[0,0,0] op_sel_hi:[1,0,1]
	v_pk_fma_f32 v[86:87], v[68:69], v[14:15], v[86:87] op_sel:[0,0,0] op_sel_hi:[1,0,1]
	v_pk_fma_f32 v[84:85], v[70:71], v[6:7], v[84:85] op_sel:[0,1,0] op_sel_hi:[1,1,1]
	v_pk_fma_f32 v[86:87], v[70:71], v[14:15], v[86:87] op_sel:[0,1,0] op_sel_hi:[1,1,1]
	v_pk_fma_f32 v[84:85], v[72:73], v[8:9], v[84:85] op_sel:[0,0,0] op_sel_hi:[1,0,1]
	v_pk_fma_f32 v[86:87], v[72:73], v[16:17], v[86:87] op_sel:[0,0,0] op_sel_hi:[1,0,1]
	v_pk_fma_f32 v[84:85], v[74:75], v[8:9], v[84:85] op_sel:[0,1,0] op_sel_hi:[1,1,1]
	v_pk_fma_f32 v[86:87], v[74:75], v[16:17], v[86:87] op_sel:[0,1,0] op_sel_hi:[1,1,1]
	s_nop 0
	v_add_f32_dpp v84, v84, v84 quad_perm:[1,0,3,2] row_mask:0xf bank_mask:0xf bound_ctrl:1
	v_add_f32_dpp v85, v85, v85 quad_perm:[1,0,3,2] row_mask:0xf bank_mask:0xf bound_ctrl:1
	v_add_f32_dpp v86, v86, v86 quad_perm:[1,0,3,2] row_mask:0xf bank_mask:0xf bound_ctrl:1
	v_add_f32_dpp v87, v87, v87 quad_perm:[1,0,3,2] row_mask:0xf bank_mask:0xf bound_ctrl:1
	v_add_f32_dpp v84, v84, v84 quad_perm:[2,3,0,1] row_mask:0xf bank_mask:0xf bound_ctrl:1
	v_add_f32_dpp v85, v85, v85 quad_perm:[2,3,0,1] row_mask:0xf bank_mask:0xf bound_ctrl:1
	v_add_f32_dpp v86, v86, v86 quad_perm:[2,3,0,1] row_mask:0xf bank_mask:0xf bound_ctrl:1
	v_add_f32_dpp v87, v87, v87 quad_perm:[2,3,0,1] row_mask:0xf bank_mask:0xf bound_ctrl:1
	v_add_f32_dpp v84, v84, v84 row_half_mirror row_mask:0xf bank_mask:0xf bound_ctrl:1
	v_add_f32_dpp v85, v85, v85 row_half_mirror row_mask:0xf bank_mask:0xf bound_ctrl:1
	v_add_f32_dpp v86, v86, v86 row_half_mirror row_mask:0xf bank_mask:0xf bound_ctrl:1
	v_add_f32_dpp v87, v87, v87 row_half_mirror row_mask:0xf bank_mask:0xf bound_ctrl:1
	ds_read_b128 v[2:5], v118 offset:33280
	ds_read_b128 v[6:9], v118 offset:33296
	ds_read_b128 v[10:13], v118 offset:512
	ds_read_b128 v[14:17], v118 offset:528
	s_waitcnt lgkmcnt(10)
	v_pk_mul_f32 v[114:115], v[26:27], v[84:85] op_sel:[0,0] op_sel_hi:[0,1] neg_lo:[0,1] neg_hi:[0,1]
	v_pk_mul_f32 v[116:117], v[26:27], v[84:85] op_sel:[1,0] op_sel_hi:[1,1] neg_lo:[0,1] neg_hi:[0,1]
	v_pk_mul_f32 v[122:123], v[28:29], v[84:85] op_sel:[0,0] op_sel_hi:[0,1] neg_lo:[0,1] neg_hi:[0,1]
	v_pk_mul_f32 v[124:125], v[28:29], v[84:85] op_sel:[1,0] op_sel_hi:[1,1] neg_lo:[0,1] neg_hi:[0,1]
	v_pk_mul_f32 v[126:127], v[30:31], v[84:85] op_sel:[0,0] op_sel_hi:[0,1] neg_lo:[0,1] neg_hi:[0,1]
	v_pk_mul_f32 v[128:129], v[30:31], v[84:85] op_sel:[1,0] op_sel_hi:[1,1] neg_lo:[0,1] neg_hi:[0,1]
	v_pk_mul_f32 v[130:131], v[32:33], v[84:85] op_sel:[0,0] op_sel_hi:[0,1] neg_lo:[0,1] neg_hi:[0,1]
	v_pk_mul_f32 v[132:133], v[32:33], v[84:85] op_sel:[1,0] op_sel_hi:[1,1] neg_lo:[0,1] neg_hi:[0,1]
	s_waitcnt lgkmcnt(7)
	v_pk_fma_f32 v[114:115], v[76:77], v[34:35], v[114:115] op_sel:[0,0,0] op_sel_hi:[0,1,1]
	v_pk_fma_f32 v[116:117], v[76:77], v[34:35], v[116:117] op_sel:[1,0,0] op_sel_hi:[1,1,1]
	v_pk_fma_f32 v[122:123], v[78:79], v[34:35], v[122:123] op_sel:[0,0,0] op_sel_hi:[0,1,1]
	v_pk_fma_f32 v[124:125], v[78:79], v[34:35], v[124:125] op_sel:[1,0,0] op_sel_hi:[1,1,1]
	v_pk_fma_f32 v[126:127], v[80:81], v[34:35], v[126:127] op_sel:[0,0,0] op_sel_hi:[0,1,1]
	v_pk_fma_f32 v[128:129], v[80:81], v[34:35], v[128:129] op_sel:[1,0,0] op_sel_hi:[1,1,1]
	v_pk_fma_f32 v[130:131], v[82:83], v[34:35], v[130:131] op_sel:[0,0,0] op_sel_hi:[0,1,1]
	v_pk_fma_f32 v[132:133], v[82:83], v[34:35], v[132:133] op_sel:[1,0,0] op_sel_hi:[1,1,1]
	s_waitcnt lgkmcnt(6)
	v_pk_fma_f32 v[86:87], v[84:85], v[0:1], v[86:87] op_sel:[0,0,0] op_sel_hi:[1,0,1] neg_lo:[1,0,0] neg_hi:[1,0,0]
	v_pk_fma_f32 v[86:87], v[34:35], v[0:1], v[86:87] op_sel:[0,1,0] op_sel_hi:[1,1,1]
	s_mov_b64 exec, s[8:9]
	ds_write2_b32 v120, v86, v87 offset0:64 offset1:96
	s_mov_b64 exec, -1
	s_waitcnt lgkmcnt(5)
	v_pk_fma_f32 v[60:61], v[60:61], v[18:19], v[114:115] op_sel:[0,0,0] op_sel_hi:[1,0,1]
	v_pk_fma_f32 v[62:63], v[62:63], v[18:19], v[116:117] op_sel:[0,1,0] op_sel_hi:[1,1,1]
	v_pk_fma_f32 v[64:65], v[64:65], v[20:21], v[122:123] op_sel:[0,0,0] op_sel_hi:[1,0,1]
	v_pk_fma_f32 v[66:67], v[66:67], v[20:21], v[124:125] op_sel:[0,1,0] op_sel_hi:[1,1,1]
	v_pk_fma_f32 v[68:69], v[68:69], v[22:23], v[126:127] op_sel:[0,0,0] op_sel_hi:[1,0,1]
	v_pk_fma_f32 v[70:71], v[70:71], v[22:23], v[128:129] op_sel:[0,1,0] op_sel_hi:[1,1,1]
	v_pk_fma_f32 v[72:73], v[72:73], v[24:25], v[130:131] op_sel:[0,0,0] op_sel_hi:[1,0,1]
	v_pk_fma_f32 v[74:75], v[74:75], v[24:25], v[132:133] op_sel:[0,1,0] op_sel_hi:[1,1,1]
	ds_read_b128 v[26:29], v118 offset:41472
	ds_read_b128 v[30:33], v118 offset:41488
	ds_read_b128 v[76:79], v118 offset:16896
	ds_read_b128 v[80:83], v118 offset:16912
	ds_read2_b32 v[34:35], v119 offset0:128 offset1:160
	ds_read2_b32 v[0:1], v121 offset0:2 offset1:34
	ds_read_b128 v[18:21], v118 offset:8704
	ds_read_b128 v[22:25], v118 offset:8720
	s_waitcnt lgkmcnt(8)
	v_pk_mul_f32 v[84:85], v[60:61], v[2:3] op_sel:[0,0] op_sel_hi:[1,0]
	v_pk_mul_f32 v[86:87], v[60:61], v[10:11] op_sel:[0,0] op_sel_hi:[1,0]
	v_pk_fma_f32 v[84:85], v[62:63], v[2:3], v[84:85] op_sel:[0,1,0] op_sel_hi:[1,1,1]
	v_pk_fma_f32 v[86:87], v[62:63], v[10:11], v[86:87] op_sel:[0,1,0] op_sel_hi:[1,1,1]
	v_pk_fma_f32 v[84:85], v[64:65], v[4:5], v[84:85] op_sel:[0,0,0] op_sel_hi:[1,0,1]
	v_pk_fma_f32 v[86:87], v[64:65], v[12:13], v[86:87] op_sel:[0,0,0] op_sel_hi:[1,0,1]
	v_pk_fma_f32 v[84:85], v[66:67], v[4:5], v[84:85] op_sel:[0,1,0] op_sel_hi:[1,1,1]
	v_pk_fma_f32 v[86:87], v[66:67], v[12:13], v[86:87] op_sel:[0,1,0] op_sel_hi:[1,1,1]
	v_pk_fma_f32 v[84:85], v[68:69], v[6:7], v[84:85] op_sel:[0,0,0] op_sel_hi:[1,0,1]
	v_pk_fma_f32 v[86:87], v[68:69], v[14:15], v[86:87] op_sel:[0,0,0] op_sel_hi:[1,0,1]
	v_pk_fma_f32 v[84:85], v[70:71], v[6:7], v[84:85] op_sel:[0,1,0] op_sel_hi:[1,1,1]
	v_pk_fma_f32 v[86:87], v[70:71], v[14:15], v[86:87] op_sel:[0,1,0] op_sel_hi:[1,1,1]
	v_pk_fma_f32 v[84:85], v[72:73], v[8:9], v[84:85] op_sel:[0,0,0] op_sel_hi:[1,0,1]
	v_pk_fma_f32 v[86:87], v[72:73], v[16:17], v[86:87] op_sel:[0,0,0] op_sel_hi:[1,0,1]
	v_pk_fma_f32 v[84:85], v[74:75], v[8:9], v[84:85] op_sel:[0,1,0] op_sel_hi:[1,1,1]
	v_pk_fma_f32 v[86:87], v[74:75], v[16:17], v[86:87] op_sel:[0,1,0] op_sel_hi:[1,1,1]
	s_nop 0
	v_add_f32_dpp v84, v84, v84 quad_perm:[1,0,3,2] row_mask:0xf bank_mask:0xf bound_ctrl:1
	v_add_f32_dpp v85, v85, v85 quad_perm:[1,0,3,2] row_mask:0xf bank_mask:0xf bound_ctrl:1
	v_add_f32_dpp v86, v86, v86 quad_perm:[1,0,3,2] row_mask:0xf bank_mask:0xf bound_ctrl:1
	v_add_f32_dpp v87, v87, v87 quad_perm:[1,0,3,2] row_mask:0xf bank_mask:0xf bound_ctrl:1
	v_add_f32_dpp v84, v84, v84 quad_perm:[2,3,0,1] row_mask:0xf bank_mask:0xf bound_ctrl:1
	v_add_f32_dpp v85, v85, v85 quad_perm:[2,3,0,1] row_mask:0xf bank_mask:0xf bound_ctrl:1
	v_add_f32_dpp v86, v86, v86 quad_perm:[2,3,0,1] row_mask:0xf bank_mask:0xf bound_ctrl:1
	v_add_f32_dpp v87, v87, v87 quad_perm:[2,3,0,1] row_mask:0xf bank_mask:0xf bound_ctrl:1
	v_add_f32_dpp v84, v84, v84 row_half_mirror row_mask:0xf bank_mask:0xf bound_ctrl:1
	v_add_f32_dpp v85, v85, v85 row_half_mirror row_mask:0xf bank_mask:0xf bound_ctrl:1
	v_add_f32_dpp v86, v86, v86 row_half_mirror row_mask:0xf bank_mask:0xf bound_ctrl:1
	v_add_f32_dpp v87, v87, v87 row_half_mirror row_mask:0xf bank_mask:0xf bound_ctrl:1
	ds_read_b128 v[2:5], v118 offset:33536
	ds_read_b128 v[6:9], v118 offset:33552
	ds_read_b128 v[10:13], v118 offset:768
	ds_read_b128 v[14:17], v118 offset:784
	s_waitcnt lgkmcnt(10)
	v_pk_mul_f32 v[114:115], v[26:27], v[84:85] op_sel:[0,0] op_sel_hi:[0,1] neg_lo:[0,1] neg_hi:[0,1]
	v_pk_mul_f32 v[116:117], v[26:27], v[84:85] op_sel:[1,0] op_sel_hi:[1,1] neg_lo:[0,1] neg_hi:[0,1]
	v_pk_mul_f32 v[122:123], v[28:29], v[84:85] op_sel:[0,0] op_sel_hi:[0,1] neg_lo:[0,1] neg_hi:[0,1]
	v_pk_mul_f32 v[124:125], v[28:29], v[84:85] op_sel:[1,0] op_sel_hi:[1,1] neg_lo:[0,1] neg_hi:[0,1]
	v_pk_mul_f32 v[126:127], v[30:31], v[84:85] op_sel:[0,0] op_sel_hi:[0,1] neg_lo:[0,1] neg_hi:[0,1]
	v_pk_mul_f32 v[128:129], v[30:31], v[84:85] op_sel:[1,0] op_sel_hi:[1,1] neg_lo:[0,1] neg_hi:[0,1]
	v_pk_mul_f32 v[130:131], v[32:33], v[84:85] op_sel:[0,0] op_sel_hi:[0,1] neg_lo:[0,1] neg_hi:[0,1]
	v_pk_mul_f32 v[132:133], v[32:33], v[84:85] op_sel:[1,0] op_sel_hi:[1,1] neg_lo:[0,1] neg_hi:[0,1]
	s_waitcnt lgkmcnt(7)
	v_pk_fma_f32 v[114:115], v[76:77], v[34:35], v[114:115] op_sel:[0,0,0] op_sel_hi:[0,1,1]
	v_pk_fma_f32 v[116:117], v[76:77], v[34:35], v[116:117] op_sel:[1,0,0] op_sel_hi:[1,1,1]
	v_pk_fma_f32 v[122:123], v[78:79], v[34:35], v[122:123] op_sel:[0,0,0] op_sel_hi:[0,1,1]
	v_pk_fma_f32 v[124:125], v[78:79], v[34:35], v[124:125] op_sel:[1,0,0] op_sel_hi:[1,1,1]
	v_pk_fma_f32 v[126:127], v[80:81], v[34:35], v[126:127] op_sel:[0,0,0] op_sel_hi:[0,1,1]
	v_pk_fma_f32 v[128:129], v[80:81], v[34:35], v[128:129] op_sel:[1,0,0] op_sel_hi:[1,1,1]
	v_pk_fma_f32 v[130:131], v[82:83], v[34:35], v[130:131] op_sel:[0,0,0] op_sel_hi:[0,1,1]
	v_pk_fma_f32 v[132:133], v[82:83], v[34:35], v[132:133] op_sel:[1,0,0] op_sel_hi:[1,1,1]
	s_waitcnt lgkmcnt(6)
	v_pk_fma_f32 v[86:87], v[84:85], v[0:1], v[86:87] op_sel:[0,0,0] op_sel_hi:[1,0,1] neg_lo:[1,0,0] neg_hi:[1,0,0]
	v_pk_fma_f32 v[86:87], v[34:35], v[0:1], v[86:87] op_sel:[0,1,0] op_sel_hi:[1,1,1]
	s_mov_b64 exec, s[8:9]
	ds_write2_b32 v120, v86, v87 offset0:128 offset1:160
	s_mov_b64 exec, -1
	s_waitcnt lgkmcnt(5)
	v_pk_fma_f32 v[60:61], v[60:61], v[18:19], v[114:115] op_sel:[0,0,0] op_sel_hi:[1,0,1]
	v_pk_fma_f32 v[62:63], v[62:63], v[18:19], v[116:117] op_sel:[0,1,0] op_sel_hi:[1,1,1]
	v_pk_fma_f32 v[64:65], v[64:65], v[20:21], v[122:123] op_sel:[0,0,0] op_sel_hi:[1,0,1]
	v_pk_fma_f32 v[66:67], v[66:67], v[20:21], v[124:125] op_sel:[0,1,0] op_sel_hi:[1,1,1]
	v_pk_fma_f32 v[68:69], v[68:69], v[22:23], v[126:127] op_sel:[0,0,0] op_sel_hi:[1,0,1]
	v_pk_fma_f32 v[70:71], v[70:71], v[22:23], v[128:129] op_sel:[0,1,0] op_sel_hi:[1,1,1]
	v_pk_fma_f32 v[72:73], v[72:73], v[24:25], v[130:131] op_sel:[0,0,0] op_sel_hi:[1,0,1]
	v_pk_fma_f32 v[74:75], v[74:75], v[24:25], v[132:133] op_sel:[0,1,0] op_sel_hi:[1,1,1]
	ds_read_b128 v[26:29], v118 offset:41728
	ds_read_b128 v[30:33], v118 offset:41744
	ds_read_b128 v[76:79], v118 offset:17152
	ds_read_b128 v[80:83], v118 offset:17168
	ds_read2_b32 v[34:35], v119 offset0:192 offset1:224
	ds_read2_b32 v[0:1], v121 offset0:3 offset1:35
	ds_read_b128 v[18:21], v118 offset:8960
	ds_read_b128 v[22:25], v118 offset:8976
	s_waitcnt lgkmcnt(8)
; #define SCAN_LDK(X, X0, X1, s_) do { const LAS float* p_ = ib + (s_) * 64 + kp; \
;                     X[0] = *(const LAS f32x4*)(p_ + 4 * CH * 64); X[1] = *(const LAS f32x4*)(p_ + 4 * CH * 64 + 4); \
;                     X0 = ib[3 * CH * 64 + (s_) * 64 + v0]; X1 = ib[3 * CH * 64 + (s_) * 64 + v1]; } while (0)
; DEVINL void rwkv_scan(LAS unsigned char* lds, const bf16_t* Prwkv, const bf16_t* Aa, const bf16_t* Gg, const bf16_t* Uu, const float* w0v, const float* a0v, const float* mu, ...
;     ...
;                 __builtin_amdgcn_s_setprio(2);
;                 SCAN_LDK(Ka, Av0, Av1, 0);
; #pragma unroll 1
;                 for (int s = 0; s < CH; s += 2) {
;                     SCAN_STEP(Ka, Av0, Av1, s, SCAN_LDK(Kb, Bv0, Bv1, s + 1));
;                     const int sn = (s + 2 < CH) ? s + 2 : CH - 1;
;                     SCAN_STEP(Kb, Bv0, Bv1, s + 1, SCAN_LDK(Ka, Av0, Av1, sn));
;                 }
;                 __builtin_amdgcn_s_setprio(0);
;     ...
;             }
;             __syncthreads();
	v_pk_mul_f32 v[84:85], v[60:61], v[2:3] op_sel:[0,0] op_sel_hi:[1,0]
	v_pk_mul_f32 v[86:87], v[60:61], v[10:11] op_sel:[0,0] op_sel_hi:[1,0]
	v_pk_fma_f32 v[84:85], v[62:63], v[2:3], v[84:85] op_sel:[0,1,0] op_sel_hi:[1,1,1]
	v_pk_fma_f32 v[86:87], v[62:63], v[10:11], v[86:87] op_sel:[0,1,0] op_sel_hi:[1,1,1]
	v_pk_fma_f32 v[84:85], v[64:65], v[4:5], v[84:85] op_sel:[0,0,0] op_sel_hi:[1,0,1]
	v_pk_fma_f32 v[86:87], v[64:65], v[12:13], v[86:87] op_sel:[0,0,0] op_sel_hi:[1,0,1]
	v_pk_fma_f32 v[84:85], v[66:67], v[4:5], v[84:85] op_sel:[0,1,0] op_sel_hi:[1,1,1]
	v_pk_fma_f32 v[86:87], v[66:67], v[12:13], v[86:87] op_sel:[0,1,0] op_sel_hi:[1,1,1]
	v_pk_fma_f32 v[84:85], v[68:69], v[6:7], v[84:85] op_sel:[0,0,0] op_sel_hi:[1,0,1]
	v_pk_fma_f32 v[86:87], v[68:69], v[14:15], v[86:87] op_sel:[0,0,0] op_sel_hi:[1,0,1]
	v_pk_fma_f32 v[84:85], v[70:71], v[6:7], v[84:85] op_sel:[0,1,0] op_sel_hi:[1,1,1]
	v_pk_fma_f32 v[86:87], v[70:71], v[14:15], v[86:87] op_sel:[0,1,0] op_sel_hi:[1,1,1]
	v_pk_fma_f32 v[84:85], v[72:73], v[8:9], v[84:85] op_sel:[0,0,0] op_sel_hi:[1,0,1]
	v_pk_fma_f32 v[86:87], v[72:73], v[16:17], v[86:87] op_sel:[0,0,0] op_sel_hi:[1,0,1]
	v_pk_fma_f32 v[84:85], v[74:75], v[8:9], v[84:85] op_sel:[0,1,0] op_sel_hi:[1,1,1]
	v_pk_fma_f32 v[86:87], v[74:75], v[16:17], v[86:87] op_sel:[0,1,0] op_sel_hi:[1,1,1]
	s_nop 0
	v_add_f32_dpp v84, v84, v84 quad_perm:[1,0,3,2] row_mask:0xf bank_mask:0xf bound_ctrl:1
	v_add_f32_dpp v85, v85, v85 quad_perm:[1,0,3,2] row_mask:0xf bank_mask:0xf bound_ctrl:1
	v_add_f32_dpp v86, v86, v86 quad_perm:[1,0,3,2] row_mask:0xf bank_mask:0xf bound_ctrl:1
	v_add_f32_dpp v87, v87, v87 quad_perm:[1,0,3,2] row_mask:0xf bank_mask:0xf bound_ctrl:1
	v_add_f32_dpp v84, v84, v84 quad_perm:[2,3,0,1] row_mask:0xf bank_mask:0xf bound_ctrl:1
	v_add_f32_dpp v85, v85, v85 quad_perm:[2,3,0,1] row_mask:0xf bank_mask:0xf bound_ctrl:1
	v_add_f32_dpp v86, v86, v86 quad_perm:[2,3,0,1] row_mask:0xf bank_mask:0xf bound_ctrl:1
	v_add_f32_dpp v87, v87, v87 quad_perm:[2,3,0,1] row_mask:0xf bank_mask:0xf bound_ctrl:1
	v_add_f32_dpp v84, v84, v84 row_half_mirror row_mask:0xf bank_mask:0xf bound_ctrl:1
	v_add_f32_dpp v85, v85, v85 row_half_mirror row_mask:0xf bank_mask:0xf bound_ctrl:1
	v_add_f32_dpp v86, v86, v86 row_half_mirror row_mask:0xf bank_mask:0xf bound_ctrl:1
	v_add_f32_dpp v87, v87, v87 row_half_mirror row_mask:0xf bank_mask:0xf bound_ctrl:1
	ds_read_b128 v[2:5], v118 offset:33792
	ds_read_b128 v[6:9], v118 offset:33808
	ds_read_b128 v[10:13], v118 offset:1024
	ds_read_b128 v[14:17], v118 offset:1040
	s_waitcnt lgkmcnt(10)
	v_pk_mul_f32 v[114:115], v[26:27], v[84:85] op_sel:[0,0] op_sel_hi:[0,1] neg_lo:[0,1] neg_hi:[0,1]
	v_pk_mul_f32 v[116:117], v[26:27], v[84:85] op_sel:[1,0] op_sel_hi:[1,1] neg_lo:[0,1] neg_hi:[0,1]
	v_pk_mul_f32 v[122:123], v[28:29], v[84:85] op_sel:[0,0] op_sel_hi:[0,1] neg_lo:[0,1] neg_hi:[0,1]
	v_pk_mul_f32 v[124:125], v[28:29], v[84:85] op_sel:[1,0] op_sel_hi:[1,1] neg_lo:[0,1] neg_hi:[0,1]
	v_pk_mul_f32 v[126:127], v[30:31], v[84:85] op_sel:[0,0] op_sel_hi:[0,1] neg_lo:[0,1] neg_hi:[0,1]
	v_pk_mul_f32 v[128:129], v[30:31], v[84:85] op_sel:[1,0] op_sel_hi:[1,1] neg_lo:[0,1] neg_hi:[0,1]
	v_pk_mul_f32 v[130:131], v[32:33], v[84:85] op_sel:[0,0] op_sel_hi:[0,1] neg_lo:[0,1] neg_hi:[0,1]
	v_pk_mul_f32 v[132:133], v[32:33], v[84:85] op_sel:[1,0] op_sel_hi:[1,1] neg_lo:[0,1] neg_hi:[0,1]
	s_waitcnt lgkmcnt(7)
	v_pk_fma_f32 v[114:115], v[76:77], v[34:35], v[114:115] op_sel:[0,0,0] op_sel_hi:[0,1,1]
	v_pk_fma_f32 v[116:117], v[76:77], v[34:35], v[116:117] op_sel:[1,0,0] op_sel_hi:[1,1,1]
	v_pk_fma_f32 v[122:123], v[78:79], v[34:35], v[122:123] op_sel:[0,0,0] op_sel_hi:[0,1,1]
	v_pk_fma_f32 v[124:125], v[78:79], v[34:35], v[124:125] op_sel:[1,0,0] op_sel_hi:[1,1,1]
	v_pk_fma_f32 v[126:127], v[80:81], v[34:35], v[126:127] op_sel:[0,0,0] op_sel_hi:[0,1,1]
	v_pk_fma_f32 v[128:129], v[80:81], v[34:35], v[128:129] op_sel:[1,0,0] op_sel_hi:[1,1,1]
	v_pk_fma_f32 v[130:131], v[82:83], v[34:35], v[130:131] op_sel:[0,0,0] op_sel_hi:[0,1,1]
	v_pk_fma_f32 v[132:133], v[82:83], v[34:35], v[132:133] op_sel:[1,0,0] op_sel_hi:[1,1,1]
	s_waitcnt lgkmcnt(6)
	v_pk_fma_f32 v[86:87], v[84:85], v[0:1], v[86:87] op_sel:[0,0,0] op_sel_hi:[1,0,1] neg_lo:[1,0,0] neg_hi:[1,0,0]
	v_pk_fma_f32 v[86:87], v[34:35], v[0:1], v[86:87] op_sel:[0,1,0] op_sel_hi:[1,1,1]
	s_mov_b64 exec, s[8:9]
	ds_write2_b32 v120, v86, v87 offset0:192 offset1:224
	s_mov_b64 exec, -1
	s_waitcnt lgkmcnt(5)
	v_pk_fma_f32 v[60:61], v[60:61], v[18:19], v[114:115] op_sel:[0,0,0] op_sel_hi:[1,0,1]
	v_pk_fma_f32 v[62:63], v[62:63], v[18:19], v[116:117] op_sel:[0,1,0] op_sel_hi:[1,1,1]
	v_pk_fma_f32 v[64:65], v[64:65], v[20:21], v[122:123] op_sel:[0,0,0] op_sel_hi:[1,0,1]
	v_pk_fma_f32 v[66:67], v[66:67], v[20:21], v[124:125] op_sel:[0,1,0] op_sel_hi:[1,1,1]
	v_pk_fma_f32 v[68:69], v[68:69], v[22:23], v[126:127] op_sel:[0,0,0] op_sel_hi:[1,0,1]
	v_pk_fma_f32 v[70:71], v[70:71], v[22:23], v[128:129] op_sel:[0,1,0] op_sel_hi:[1,1,1]
	v_pk_fma_f32 v[72:73], v[72:73], v[24:25], v[130:131] op_sel:[0,0,0] op_sel_hi:[1,0,1]
	v_pk_fma_f32 v[74:75], v[74:75], v[24:25], v[132:133] op_sel:[0,1,0] op_sel_hi:[1,1,1]
	v_add_u32_e32 v118, 0x400, v118
	v_add_u32_e32 v119, 0x400, v119
	v_add_u32_e32 v120, 0x400, v120
	v_add_u32_e32 v121, 16, v121
	s_add_i32 s44, s44, 1
	s_cmp_lt_u32 s44, 8
	s_cbranch_scc1 .Lscan_iter
	s_setprio 0
	s_add_i32 s30, s30, 1
	s_cmp_eq_u32 s30, 64
	s_waitcnt lgkmcnt(0)
	s_barrier
	s_cbranch_scc0 .Lscan_chunk
	s_branch .LBB0_1087
